# non-temporal stores for the residual-stream rows written in phases 10 and 16
# speedup vs baseline: 1.0219x; 1.0058x over previous
.LBB0_980:
	v_lshl_add_u64 v[94:95], s[8:9], 0, v[32:33]
	v_add_co_u32_e64 v98, s[4:5], s19, v94
	s_add_i32 s14, s13, s17
	s_nop 0
	v_addc_co_u32_e64 v99, s[4:5], 0, v95, s[4:5]
	v_add_co_u32_e32 v96, vcc, 0x4000000, v94
	v_add_co_u32_e64 v100, s[4:5], s20, v94
	v_lshl_add_u64 v[92:93], s[10:11], 0, v[32:33]
	s_ashr_i32 s15, s14, 31
	v_addc_co_u32_e64 v101, s[4:5], 0, v95, s[4:5]
	v_addc_co_u32_e32 v97, vcc, 0, v95, vcc
	global_load_dwordx2 v[110:111], v[92:93], off nt
	global_load_dwordx2 v[112:113], v[92:93], off offset:512 nt
	global_load_dwordx2 v[114:115], v[92:93], off offset:1024 nt
	global_load_dwordx2 v[116:117], v[92:93], off offset:1536 nt
	s_lshl_b64 s[4:5], s[14:15], 11
	global_load_dwordx2 v[118:119], v[96:97], off offset:1536 nt
	global_load_dwordx2 v[120:121], v[96:97], off nt
	global_load_dwordx2 v[122:123], v[96:97], off offset:512 nt
	global_load_dwordx2 v[124:125], v[96:97], off offset:1024 nt
	v_lshl_add_u64 v[126:127], v[84:85], 0, s[4:5]
	v_lshl_add_u64 v[102:103], v[82:83], 0, s[4:5]
	global_load_dwordx2 v[128:129], v[102:103], off nt
	global_load_dwordx2 v[130:131], v[102:103], off offset:512 nt
	global_load_dwordx2 v[132:133], v[102:103], off offset:1024 nt
	global_load_dwordx2 v[134:135], v[102:103], off offset:1536 nt
	global_load_dwordx2 v[136:137], v[126:127], off offset:1536 nt
	global_load_dwordx2 v[138:139], v[126:127], off nt
	global_load_dwordx2 v[140:141], v[126:127], off offset:512 nt
	s_nop 0
	global_load_dwordx2 v[126:127], v[126:127], off offset:1024 nt
	v_lshl_add_u64 v[94:95], v[86:87], 0, s[4:5]
	v_lshl_add_u64 v[96:97], v[88:89], 0, s[4:5]
	s_add_i32 s17, s17, 2
	s_add_u32 s8, s8, 0x1000
	s_addc_u32 s9, s9, 0
	s_add_u32 s10, s10, 0x1000
	s_addc_u32 s11, s11, 0
	s_cmp_lt_i32 s17, s16
	s_waitcnt vmcnt(15)
	v_lshlrev_b32_e32 v142, 16, v110
	v_and_b32_e32 v143, 0xffff0000, v110
	s_waitcnt vmcnt(11)
	v_lshlrev_b32_e32 v151, 16, v118
	s_waitcnt vmcnt(10)
	v_lshlrev_b32_e32 v154, 16, v120
	v_and_b32_e32 v155, 0xffff0000, v120
	v_lshlrev_b32_e32 v120, 16, v121
	v_and_b32_e32 v121, 0xffff0000, v121
	s_waitcnt vmcnt(9)
	v_lshlrev_b32_e32 v157, 16, v123
	v_lshlrev_b32_e32 v156, 16, v122
	v_and_b32_e32 v123, 0xffff0000, v123
	v_and_b32_e32 v122, 0xffff0000, v122
	s_waitcnt vmcnt(8)
	v_lshlrev_b32_e32 v158, 16, v124
	v_and_b32_e32 v159, 0xffff0000, v124
	v_lshlrev_b32_e32 v124, 16, v125
	v_and_b32_e32 v125, 0xffff0000, v125
	s_waitcnt vmcnt(3)
	v_lshlrev_b32_e32 v169, 16, v136
	v_mul_f32_e32 v150, v121, v121
	v_pk_mul_f32 v[172:173], v[122:123], v[122:123]
	v_mul_f32_e32 v168, v155, v155
	v_mov_b32_e32 v175, v151
	v_mul_f32_e32 v174, v125, v125
	v_mov_b32_e32 v176, v156
	v_mov_b32_e32 v177, v122
	v_mov_b32_e32 v122, v157
	s_waitcnt vmcnt(2)
	v_lshlrev_b32_e32 v178, 16, v138
	v_and_b32_e32 v179, 0xffff0000, v138
	v_lshlrev_b32_e32 v138, 16, v139
	v_and_b32_e32 v139, 0xffff0000, v139
	s_waitcnt vmcnt(1)
	v_lshlrev_b32_e32 v181, 16, v141
	v_lshlrev_b32_e32 v180, 16, v140
	v_and_b32_e32 v141, 0xffff0000, v141
	v_and_b32_e32 v140, 0xffff0000, v140
	v_pk_fma_f32 v[184:185], v[120:121], v[120:121], v[150:151] op_sel_hi:[1,1,0]
	v_pk_fma_f32 v[156:157], v[156:157], v[156:157], v[172:173]
	v_pk_fma_f32 v[172:173], v[154:155], v[154:155], v[168:169] op_sel_hi:[1,1,0]
	v_and_b32_e32 v153, 0xffff0000, v118
	v_lshlrev_b32_e32 v118, 16, v119
	v_and_b32_e32 v119, 0xffff0000, v119
	v_and_b32_e32 v171, 0xffff0000, v136
	v_mul_f32_e32 v170, v159, v159
	v_pk_fma_f32 v[188:189], v[124:125], v[124:125], v[174:175] op_sel_hi:[1,1,0]
	v_mul_f32_e32 v168, v139, v139
	v_pk_mul_f32 v[192:193], v[140:141], v[140:141]
	v_mul_f32_e32 v194, v179, v179
	v_mov_b32_e32 v195, v169
	v_mov_b32_e32 v150, v172
	v_mov_b32_e32 v174, v184
	v_mul_f32_e32 v109, v153, v153
	v_mul_f32_e32 v191, v118, v118
	v_mul_f32_e32 v197, v119, v119
	v_mov_b32_e32 v152, v151
	s_waitcnt vmcnt(0)
	v_lshlrev_b32_e32 v182, 16, v126
	v_and_b32_e32 v183, 0xffff0000, v126
	v_lshlrev_b32_e32 v126, 16, v127
	v_and_b32_e32 v127, 0xffff0000, v127
	v_pk_fma_f32 v[186:187], v[158:159], v[158:159], v[170:171] op_sel_hi:[1,1,0]
	v_mov_b32_e32 v200, v180
	v_mov_b32_e32 v201, v140
	v_mov_b32_e32 v140, v181
	v_pk_add_f32 v[172:173], v[172:173], v[184:185]
	v_pk_add_f32 v[156:157], v[156:157], v[156:157] op_sel:[0,1] op_sel_hi:[1,0]
	v_pk_fma_f32 v[184:185], v[138:139], v[138:139], v[168:169] op_sel_hi:[1,1,0]
	v_pk_fma_f32 v[180:181], v[180:181], v[180:181], v[192:193]
	v_pk_fma_f32 v[192:193], v[178:179], v[178:179], v[194:195] op_sel_hi:[1,1,0]
	v_pk_mul_f32 v[150:151], v[150:151], v[174:175]
	v_lshlrev_b32_e32 v136, 16, v137
	v_and_b32_e32 v137, 0xffff0000, v137
	v_mul_f32_e32 v196, v183, v183
	v_mul_f32_e32 v198, v127, v127
	v_mov_b32_e32 v187, v191
	v_mov_b32_e32 v189, v197
	v_mov_b32_e32 v157, v109
	v_mov_b32_e32 v168, v192
	v_mov_b32_e32 v194, v184
	v_mov_b32_e32 v173, v151
	v_mul_f32_e32 v202, v171, v171
	v_mul_f32_e32 v203, v136, v136
	v_mul_f32_e32 v204, v137, v137
	v_pk_fma_f32 v[196:197], v[182:183], v[182:183], v[196:197] op_sel_hi:[1,1,0]
	v_pk_fma_f32 v[198:199], v[126:127], v[126:127], v[198:199] op_sel_hi:[1,1,0]
	v_pk_add_f32 v[174:175], v[186:187], v[188:189]
	v_pk_add_f32 v[184:185], v[192:193], v[184:185]
	v_pk_add_f32 v[180:181], v[180:181], v[180:181] op_sel:[0,1] op_sel_hi:[1,0]
	v_pk_mul_f32 v[150:151], v[168:169], v[194:195]
	v_pk_add_f32 v[156:157], v[172:173], v[156:157]
	v_mov_b32_e32 v197, v203
	v_mov_b32_e32 v199, v204
	v_mov_b32_e32 v181, v202
	v_mov_b32_e32 v185, v151
	v_pk_add_f32 v[150:151], v[156:157], v[174:175]
	v_mov_b32_e32 v170, v169
	v_pk_add_f32 v[168:169], v[196:197], v[198:199]
	v_pk_add_f32 v[156:157], v[184:185], v[180:181]
	v_add_f32_e32 v109, v150, v151
	v_pk_add_f32 v[150:151], v[156:157], v[168:169]
	ds_bpermute_b32 v157, v91, v109
	v_mov_b32_e32 v156, v150
	v_lshlrev_b32_e32 v110, 16, v111
	v_and_b32_e32 v111, 0xffff0000, v111
	v_lshlrev_b32_e32 v144, 16, v112
	s_waitcnt lgkmcnt(0)
	v_add_f32_e32 v109, v109, v157
	ds_bpermute_b32 v150, v104, v109
	v_and_b32_e32 v145, 0xffff0000, v112
	v_lshlrev_b32_e32 v112, 16, v113
	v_and_b32_e32 v113, 0xffff0000, v113
	v_lshlrev_b32_e32 v146, 16, v114
	s_waitcnt lgkmcnt(0)
	v_add_f32_e32 v109, v109, v150
	ds_bpermute_b32 v150, v105, v109
	v_and_b32_e32 v147, 0xffff0000, v114
	v_lshlrev_b32_e32 v114, 16, v115
	v_and_b32_e32 v115, 0xffff0000, v115
	v_lshlrev_b32_e32 v148, 16, v116
	s_waitcnt lgkmcnt(0)
	v_add_f32_e32 v109, v109, v150
	ds_bpermute_b32 v150, v106, v109
	v_and_b32_e32 v149, 0xffff0000, v116
	v_lshlrev_b32_e32 v116, 16, v117
	v_and_b32_e32 v117, 0xffff0000, v117
	v_lshlrev_b32_e32 v160, 16, v128
	s_waitcnt lgkmcnt(0)
	v_add_f32_e32 v109, v109, v150
	ds_bpermute_b32 v150, v107, v109
	v_and_b32_e32 v161, 0xffff0000, v128
	v_lshlrev_b32_e32 v128, 16, v129
	v_and_b32_e32 v129, 0xffff0000, v129
	v_lshlrev_b32_e32 v162, 16, v130
	s_waitcnt lgkmcnt(0)
	v_add_f32_e32 v109, v109, v150
	ds_bpermute_b32 v150, v108, v109
	v_and_b32_e32 v163, 0xffff0000, v130
	v_lshlrev_b32_e32 v130, 16, v131
	v_and_b32_e32 v131, 0xffff0000, v131
	v_lshlrev_b32_e32 v164, 16, v132
	s_waitcnt lgkmcnt(0)
	v_add_f32_e32 v109, v109, v150
	v_fmamk_f32 v109, v109, 0x3a800000, v90
	v_mul_f32_e32 v150, 0x4b800000, v109
	v_cmp_gt_f32_e32 vcc, s18, v109
	v_and_b32_e32 v165, 0xffff0000, v132
	v_lshlrev_b32_e32 v132, 16, v133
	v_cndmask_b32_e32 v109, v109, v150, vcc
	v_rsq_f32_e32 v109, v109
	v_and_b32_e32 v133, 0xffff0000, v133
	v_lshlrev_b32_e32 v166, 16, v134
	v_and_b32_e32 v167, 0xffff0000, v134
	v_mul_f32_e32 v150, 0x45800000, v109
	v_cndmask_b32_e32 v150, v109, v150, vcc
	v_pk_mul_f32 v[154:155], v[150:151], v[154:155] op_sel_hi:[0,1]
	v_pk_mul_f32 v[120:121], v[150:151], v[120:121] op_sel_hi:[0,1]
	v_pk_mul_f32 v[168:169], v[150:151], v[176:177] op_sel_hi:[0,1]
	v_pk_mul_f32 v[122:123], v[150:151], v[122:123] op_sel_hi:[0,1]
	v_pk_mul_f32 v[158:159], v[150:151], v[158:159] op_sel_hi:[0,1]
	v_pk_mul_f32 v[124:125], v[150:151], v[124:125] op_sel_hi:[0,1]
	v_pk_mul_f32 v[152:153], v[150:151], v[152:153] op_sel_hi:[0,1]
	v_pk_mul_f32 v[118:119], v[150:151], v[118:119] op_sel_hi:[0,1]
	v_pk_fma_f32 v[110:111], v[38:39], v[120:121], v[110:111]
	v_pk_fma_f32 v[120:121], v[40:41], v[154:155], v[142:143]
	v_pk_fma_f32 v[112:113], v[46:47], v[122:123], v[112:113]
	v_pk_fma_f32 v[122:123], v[48:49], v[168:169], v[144:145]
	v_pk_fma_f32 v[114:115], v[58:59], v[124:125], v[114:115]
	v_pk_fma_f32 v[124:125], v[60:61], v[158:159], v[146:147]
	v_pk_fma_f32 v[116:117], v[70:71], v[118:119], v[116:117]
	v_pk_fma_f32 v[118:119], v[72:73], v[152:153], v[148:149]
	v_cvt_pk_bf16_f32 v120, v120, v121
	v_cvt_pk_bf16_f32 v121, v110, v111
	v_cvt_pk_bf16_f32 v110, v122, v123
	v_cvt_pk_bf16_f32 v111, v112, v113
	v_cvt_pk_bf16_f32 v112, v124, v125
	v_cvt_pk_bf16_f32 v113, v114, v115
	v_cvt_pk_bf16_f32 v114, v118, v119
	v_cvt_pk_bf16_f32 v115, v116, v117
	global_store_dwordx2 v[92:93], v[120:121], off nt
	global_store_dwordx2 v[92:93], v[110:111], off offset:512 nt
	global_store_dwordx2 v[92:93], v[112:113], off offset:1024 nt
	v_lshlrev_b32_e32 v119, 16, v121
	v_lshlrev_b32_e32 v118, 16, v120
	v_and_b32_e32 v121, 0xffff0000, v121
	v_and_b32_e32 v120, 0xffff0000, v120
	v_lshlrev_b32_e32 v123, 16, v111
	v_lshlrev_b32_e32 v122, 16, v110
	v_and_b32_e32 v111, 0xffff0000, v111
	v_and_b32_e32 v110, 0xffff0000, v110
	v_lshlrev_b32_e32 v116, 16, v112
	v_and_b32_e32 v117, 0xffff0000, v112
	global_store_dwordx2 v[92:93], v[114:115], off offset:1536 nt
	v_lshlrev_b32_e32 v92, 16, v114
	v_lshlrev_b32_e32 v112, 16, v113
	v_pk_mul_f32 v[124:125], v[120:121], v[120:121]
	v_pk_mul_f32 v[142:143], v[110:111], v[110:111]
	v_and_b32_e32 v113, 0xffff0000, v113
	v_mul_f32_e32 v93, v116, v116
	v_mul_f32_e32 v145, v117, v117
	v_mul_f32_e32 v146, v112, v112
	v_mov_b32_e32 v144, v92
	v_mov_b32_e32 v152, v118
	v_mov_b32_e32 v153, v120
	v_mov_b32_e32 v120, v119
	v_mov_b32_e32 v154, v122
	v_mov_b32_e32 v155, v110
	v_mov_b32_e32 v110, v123
	v_pk_fma_f32 v[118:119], v[118:119], v[118:119], v[124:125]
	v_pk_fma_f32 v[122:123], v[122:123], v[122:123], v[142:143]
	v_and_b32_e32 v109, 0xffff0000, v114
	v_lshlrev_b32_e32 v114, 16, v115
	v_and_b32_e32 v115, 0xffff0000, v115
	v_pk_fma_f32 v[124:125], v[112:113], v[112:113], v[146:147] op_sel_hi:[1,1,0]
	v_pk_add_f32 v[142:143], v[92:93], v[144:145]
	v_pk_add_f32 v[118:119], v[118:119], v[118:119] op_sel_hi:[0,1]
	v_pk_add_f32 v[122:123], v[122:123], v[122:123] op_sel_hi:[0,1]
	v_mul_f32_e32 v148, v92, v92
	v_mul_f32_e32 v124, v109, v109
	v_mov_b32_e32 v149, v143
	v_mul_f32_e32 v118, v114, v114
	v_mul_f32_e32 v122, v115, v115
	v_pk_add_f32 v[124:125], v[148:149], v[124:125]
	v_pk_add_f32 v[118:119], v[118:119], v[122:123]
	v_mov_b32_e32 v93, v109
	v_pk_add_f32 v[118:119], v[124:125], v[118:119]
	v_lshlrev_b32_e32 v134, 16, v135
	v_mov_b32_e32 v157, v118
	v_mov_b32_e32 v118, v151
	v_pk_add_f32 v[118:119], v[156:157], v[118:119]
	ds_bpermute_b32 v123, v91, v119
	ds_bpermute_b32 v122, v91, v118
	v_and_b32_e32 v135, 0xffff0000, v135
	s_waitcnt lgkmcnt(0)
	v_pk_add_f32 v[118:119], v[118:119], v[122:123]
	ds_bpermute_b32 v123, v104, v119
	ds_bpermute_b32 v122, v104, v118
	s_waitcnt lgkmcnt(0)
	v_pk_add_f32 v[118:119], v[118:119], v[122:123]
	ds_bpermute_b32 v123, v105, v119
	ds_bpermute_b32 v122, v105, v118
	s_waitcnt lgkmcnt(0)
	v_pk_add_f32 v[118:119], v[118:119], v[122:123]
	ds_bpermute_b32 v123, v106, v119
	ds_bpermute_b32 v122, v106, v118
	s_waitcnt lgkmcnt(0)
	v_pk_add_f32 v[118:119], v[118:119], v[122:123]
	ds_bpermute_b32 v123, v107, v119
	ds_bpermute_b32 v122, v107, v118
	s_waitcnt lgkmcnt(0)
	v_pk_add_f32 v[118:119], v[118:119], v[122:123]
	ds_bpermute_b32 v123, v108, v119
	ds_bpermute_b32 v122, v108, v118
	s_waitcnt lgkmcnt(0)
	v_pk_add_f32 v[118:119], v[118:119], v[122:123]
	s_nop 0
	v_pk_fma_f32 v[118:119], v[118:119], s[12:13], v[90:91] op_sel_hi:[1,0,0]
	s_nop 0
	v_mul_f32_e32 v109, 0x4b800000, v119
	v_mul_f32_e32 v122, 0x4b800000, v118
	v_cmp_gt_f32_e32 vcc, s18, v118
	v_cmp_gt_f32_e64 s[4:5], s18, v119
	s_nop 0
	v_cndmask_b32_e32 v118, v118, v122, vcc
	v_cndmask_b32_e64 v109, v119, v109, s[4:5]
	v_rsq_f32_e32 v109, v109
	v_rsq_f32_e32 v119, v118
	v_mul_f32_e32 v118, 0x45800000, v109
	v_mul_f32_e32 v122, 0x45800000, v119
	v_cndmask_b32_e64 v118, v109, v118, s[4:5]
	v_cndmask_b32_e32 v122, v119, v122, vcc
	v_pk_mul_f32 v[124:125], v[118:119], v[152:153] op_sel_hi:[0,1]
	v_pk_mul_f32 v[120:121], v[118:119], v[120:121] op_sel_hi:[0,1]
	v_pk_mul_f32 v[142:143], v[118:119], v[154:155] op_sel_hi:[0,1]
	v_pk_mul_f32 v[110:111], v[118:119], v[110:111] op_sel_hi:[0,1]
	v_pk_mul_f32 v[116:117], v[118:119], v[116:117] op_sel_hi:[0,1]
	v_pk_mul_f32 v[112:113], v[118:119], v[112:113] op_sel_hi:[0,1]
	v_pk_mul_f32 v[92:93], v[118:119], v[92:93] op_sel_hi:[0,1]
	v_pk_mul_f32 v[114:115], v[118:119], v[114:115] op_sel_hi:[0,1]
	v_pk_mul_f32 v[118:119], v[122:123], v[178:179] op_sel_hi:[0,1]
	v_pk_mul_f32 v[138:139], v[122:123], v[138:139] op_sel_hi:[0,1]
	v_pk_mul_f32 v[144:145], v[122:123], v[200:201] op_sel_hi:[0,1]
	v_pk_mul_f32 v[140:141], v[122:123], v[140:141] op_sel_hi:[0,1]
	v_pk_mul_f32 v[146:147], v[122:123], v[182:183] op_sel_hi:[0,1]
	v_pk_mul_f32 v[126:127], v[122:123], v[126:127] op_sel_hi:[0,1]
	v_pk_mul_f32 v[148:149], v[122:123], v[170:171] op_sel_hi:[0,1]
	v_pk_mul_f32 v[122:123], v[122:123], v[136:137] op_sel_hi:[0,1]
	v_pk_fma_f32 v[136:137], v[34:35], v[120:121], v[18:19]
	v_pk_fma_f32 v[150:151], v[36:37], v[124:125], v[16:17]
	v_pk_fma_f32 v[152:153], v[50:51], v[110:111], v[2:3]
	v_pk_fma_f32 v[110:111], v[54:55], v[110:111], v[10:11]
	v_pk_fma_f32 v[156:157], v[62:63], v[112:113], v[6:7]
	v_pk_fma_f32 v[158:159], v[64:65], v[116:117], v[4:5]
	v_pk_fma_f32 v[168:169], v[74:75], v[114:115], v[22:23]
	v_pk_fma_f32 v[170:171], v[76:77], v[92:93], v[20:21]
	v_pk_fma_f32 v[114:115], v[78:79], v[114:115], v[30:31]
	v_pk_fma_f32 v[92:93], v[80:81], v[92:93], v[28:29]
	v_pk_fma_f32 v[128:129], v[38:39], v[138:139], v[128:129]
	v_pk_fma_f32 v[118:119], v[40:41], v[118:119], v[160:161]
	v_pk_fma_f32 v[130:131], v[46:47], v[140:141], v[130:131]
	v_pk_fma_f32 v[138:139], v[48:49], v[144:145], v[162:163]
	v_pk_fma_f32 v[126:127], v[58:59], v[126:127], v[132:133]
	v_pk_fma_f32 v[122:123], v[70:71], v[122:123], v[134:135]
	v_pk_fma_f32 v[134:135], v[72:73], v[148:149], v[166:167]
	v_pk_fma_f32 v[120:121], v[42:43], v[120:121], v[26:27]
	v_pk_fma_f32 v[124:125], v[44:45], v[124:125], v[24:25]
	v_pk_fma_f32 v[154:155], v[52:53], v[142:143], v[0:1]
	v_pk_fma_f32 v[142:143], v[56:57], v[142:143], v[8:9]
	v_pk_fma_f32 v[112:113], v[66:67], v[112:113], v[14:15]
	v_pk_fma_f32 v[116:117], v[68:69], v[116:117], v[12:13]
	v_pk_fma_f32 v[132:133], v[60:61], v[146:147], v[164:165]
	v_cvt_pk_bf16_f32 v140, v150, v151
	v_cvt_pk_bf16_f32 v141, v136, v137
	v_cvt_pk_bf16_f32 v137, v110, v111
	v_cvt_pk_bf16_f32 v110, v158, v159
	v_cvt_pk_bf16_f32 v111, v156, v157
	v_cvt_pk_bf16_f32 v92, v92, v93
	v_cvt_pk_bf16_f32 v93, v114, v115
	v_cvt_pk_bf16_f32 v114, v118, v119
	v_cvt_pk_bf16_f32 v115, v128, v129
	v_cvt_pk_bf16_f32 v118, v138, v139
	v_cvt_pk_bf16_f32 v119, v130, v131
	v_cvt_pk_bf16_f32 v129, v126, v127
	v_cvt_pk_bf16_f32 v126, v134, v135
	v_cvt_pk_bf16_f32 v127, v122, v123
	v_cvt_pk_bf16_f32 v124, v124, v125
	v_cvt_pk_bf16_f32 v125, v120, v121
	v_cvt_pk_bf16_f32 v120, v154, v155
	v_cvt_pk_bf16_f32 v121, v152, v153
	v_cvt_pk_bf16_f32 v136, v142, v143
	v_cvt_pk_bf16_f32 v116, v116, v117
	v_cvt_pk_bf16_f32 v117, v112, v113
	v_cvt_pk_bf16_f32 v112, v170, v171
	v_cvt_pk_bf16_f32 v113, v168, v169
	v_cvt_pk_bf16_f32 v128, v132, v133
	global_store_dwordx2 v[98:99], v[140:141], off
	global_store_dwordx2 v[100:101], v[124:125], off
	global_store_dwordx2 v[98:99], v[120:121], off offset:512
	global_store_dwordx2 v[100:101], v[136:137], off offset:512
	global_store_dwordx2 v[98:99], v[110:111], off offset:1024
	global_store_dwordx2 v[100:101], v[116:117], off offset:1024
	global_store_dwordx2 v[98:99], v[112:113], off offset:1536
	global_store_dwordx2 v[100:101], v[92:93], off offset:1536
	global_store_dwordx2 v[102:103], v[114:115], off nt
	global_store_dwordx2 v[102:103], v[118:119], off offset:512 nt
	global_store_dwordx2 v[102:103], v[128:129], off offset:1024 nt
	global_store_dwordx2 v[102:103], v[126:127], off offset:1536 nt
	v_lshlrev_b32_e32 v103, 16, v115
	v_lshlrev_b32_e32 v102, 16, v114
	v_and_b32_e32 v111, 0xffff0000, v115
	v_and_b32_e32 v110, 0xffff0000, v114
	v_and_b32_e32 v115, 0xffff0000, v119
	v_and_b32_e32 v114, 0xffff0000, v118
	v_lshlrev_b32_e32 v92, 16, v128
	v_and_b32_e32 v93, 0xffff0000, v128
	v_lshlrev_b32_e32 v98, 16, v126
	v_lshlrev_b32_e32 v113, 16, v119
	v_lshlrev_b32_e32 v112, 16, v118
	v_lshlrev_b32_e32 v116, 16, v129
	v_pk_mul_f32 v[118:119], v[110:111], v[110:111]
	v_pk_mul_f32 v[120:121], v[114:115], v[114:115]
	v_and_b32_e32 v117, 0xffff0000, v129
	v_mul_f32_e32 v99, v92, v92
	v_mul_f32_e32 v123, v93, v93
	v_mul_f32_e32 v124, v116, v116
	v_mov_b32_e32 v122, v98
	v_mov_b32_e32 v128, v102
	v_mov_b32_e32 v129, v110
	v_mov_b32_e32 v110, v103
	v_mov_b32_e32 v130, v112
	v_mov_b32_e32 v131, v114
	v_mov_b32_e32 v114, v113
	v_pk_fma_f32 v[102:103], v[102:103], v[102:103], v[118:119]
	v_pk_fma_f32 v[112:113], v[112:113], v[112:113], v[120:121]
	v_and_b32_e32 v109, 0xffff0000, v126
	v_lshlrev_b32_e32 v100, 16, v127
	v_and_b32_e32 v101, 0xffff0000, v127
	v_pk_fma_f32 v[118:119], v[116:117], v[116:117], v[124:125] op_sel_hi:[1,1,0]
	v_pk_add_f32 v[120:121], v[98:99], v[122:123]
	v_pk_add_f32 v[102:103], v[102:103], v[102:103] op_sel_hi:[0,1]
	v_pk_add_f32 v[112:113], v[112:113], v[112:113] op_sel_hi:[0,1]
	v_mul_f32_e32 v126, v98, v98
	v_mul_f32_e32 v118, v109, v109
	v_mov_b32_e32 v127, v121
	v_mul_f32_e32 v102, v100, v100
	v_mul_f32_e32 v112, v101, v101
	v_pk_add_f32 v[118:119], v[126:127], v[118:119]
	v_pk_add_f32 v[102:103], v[102:103], v[112:113]
	v_mov_b32_e32 v99, v109
	v_pk_add_f32 v[102:103], v[118:119], v[102:103]
	s_nop 0
	v_add_f32_e32 v102, v102, v103
	ds_bpermute_b32 v103, v91, v102
	s_waitcnt lgkmcnt(0)
	v_add_f32_e32 v102, v102, v103
	ds_bpermute_b32 v103, v104, v102
	s_waitcnt lgkmcnt(0)
	v_add_f32_e32 v102, v102, v103
	ds_bpermute_b32 v103, v105, v102
	s_waitcnt lgkmcnt(0)
	v_add_f32_e32 v102, v102, v103
	ds_bpermute_b32 v103, v106, v102
	s_waitcnt lgkmcnt(0)
	v_add_f32_e32 v102, v102, v103
	ds_bpermute_b32 v103, v107, v102
	s_waitcnt lgkmcnt(0)
	v_add_f32_e32 v102, v102, v103
	ds_bpermute_b32 v103, v108, v102
	s_waitcnt lgkmcnt(0)
	v_add_f32_e32 v102, v102, v103
	v_fmamk_f32 v102, v102, 0x3a800000, v90
	v_mul_f32_e32 v103, 0x4b800000, v102
	v_cmp_gt_f32_e32 vcc, s18, v102
	s_nop 1
	v_cndmask_b32_e32 v102, v102, v103, vcc
	v_rsq_f32_e32 v102, v102
	s_nop 0
	v_mul_f32_e32 v103, 0x45800000, v102
	v_cndmask_b32_e32 v102, v102, v103, vcc
	v_pk_mul_f32 v[112:113], v[102:103], v[128:129] op_sel_hi:[0,1]
	v_pk_mul_f32 v[110:111], v[102:103], v[110:111] op_sel_hi:[0,1]
	v_pk_mul_f32 v[118:119], v[102:103], v[130:131] op_sel_hi:[0,1]
	v_pk_mul_f32 v[114:115], v[102:103], v[114:115] op_sel_hi:[0,1]
	v_pk_mul_f32 v[92:93], v[102:103], v[92:93] op_sel_hi:[0,1]
	v_pk_mul_f32 v[116:117], v[102:103], v[116:117] op_sel_hi:[0,1]
	v_pk_mul_f32 v[98:99], v[102:103], v[98:99] op_sel_hi:[0,1]
	v_pk_mul_f32 v[100:101], v[102:103], v[100:101] op_sel_hi:[0,1]
	v_pk_fma_f32 v[102:103], v[34:35], v[110:111], v[18:19]
	v_pk_fma_f32 v[120:121], v[36:37], v[112:113], v[16:17]
	v_pk_fma_f32 v[110:111], v[42:43], v[110:111], v[26:27]
	v_pk_fma_f32 v[112:113], v[44:45], v[112:113], v[24:25]
	v_pk_fma_f32 v[122:123], v[50:51], v[114:115], v[2:3]
	v_pk_fma_f32 v[124:125], v[52:53], v[118:119], v[0:1]
	v_pk_fma_f32 v[114:115], v[54:55], v[114:115], v[10:11]
	v_pk_fma_f32 v[118:119], v[56:57], v[118:119], v[8:9]
	v_pk_fma_f32 v[126:127], v[62:63], v[116:117], v[6:7]
	v_pk_fma_f32 v[128:129], v[64:65], v[92:93], v[4:5]
	v_pk_fma_f32 v[116:117], v[66:67], v[116:117], v[14:15]
	v_pk_fma_f32 v[92:93], v[68:69], v[92:93], v[12:13]
	v_pk_fma_f32 v[130:131], v[74:75], v[100:101], v[22:23]
	v_pk_fma_f32 v[132:133], v[76:77], v[98:99], v[20:21]
	v_pk_fma_f32 v[100:101], v[78:79], v[100:101], v[30:31]
	v_pk_fma_f32 v[98:99], v[80:81], v[98:99], v[28:29]
	v_cvt_pk_bf16_f32 v120, v120, v121
	v_cvt_pk_bf16_f32 v121, v102, v103
	v_cvt_pk_bf16_f32 v102, v112, v113
	v_cvt_pk_bf16_f32 v103, v110, v111
	v_cvt_pk_bf16_f32 v110, v124, v125
	v_cvt_pk_bf16_f32 v111, v122, v123
	v_cvt_pk_bf16_f32 v112, v118, v119
	v_cvt_pk_bf16_f32 v113, v114, v115
	v_cvt_pk_bf16_f32 v114, v128, v129
	v_cvt_pk_bf16_f32 v115, v126, v127
	v_cvt_pk_bf16_f32 v92, v92, v93
	v_cvt_pk_bf16_f32 v93, v116, v117
	v_cvt_pk_bf16_f32 v116, v132, v133
	v_cvt_pk_bf16_f32 v117, v130, v131
	v_cvt_pk_bf16_f32 v98, v98, v99
	v_cvt_pk_bf16_f32 v99, v100, v101
	global_store_dwordx2 v[94:95], v[120:121], off
	global_store_dwordx2 v[96:97], v[102:103], off
	global_store_dwordx2 v[94:95], v[110:111], off offset:512
	global_store_dwordx2 v[96:97], v[112:113], off offset:512
	global_store_dwordx2 v[94:95], v[114:115], off offset:1024
	global_store_dwordx2 v[96:97], v[92:93], off offset:1024
	global_store_dwordx2 v[94:95], v[116:117], off offset:1536
	global_store_dwordx2 v[96:97], v[98:99], off offset:1536
	s_cbranch_scc1 .LBB0_980

.LBB0_1498:
	v_lshl_add_u64 v[60:61], s[6:7], 0, v[16:17]
	v_add_co_u32_e64 v80, s[0:1], s17, v60
	v_lshl_add_u64 v[62:63], s[8:9], 0, v[16:17]
	s_nop 0
	v_addc_co_u32_e64 v81, s[0:1], 0, v61, s[0:1]
	s_add_i32 s12, s15, s14
	v_add_co_u32_e32 v64, vcc, 0x4000000, v60
	global_load_dwordx2 v[72:73], v[62:63], off nt
	global_load_dwordx2 v[74:75], v[62:63], off offset:512 nt
	global_load_dwordx2 v[76:77], v[62:63], off offset:1024 nt
	global_load_dwordx2 v[78:79], v[62:63], off offset:1536 nt
	v_add_co_u32_e64 v62, s[0:1], s18, v60
	s_ashr_i32 s13, s12, 31
	s_nop 0
	v_addc_co_u32_e64 v63, s[0:1], 0, v61, s[0:1]
	v_addc_co_u32_e32 v65, vcc, 0, v61, vcc
	s_lshl_b64 s[0:1], s[12:13], 11
	global_load_dwordx2 v[82:83], v[64:65], off offset:1536 nt
	global_load_dwordx2 v[84:85], v[64:65], off nt
	global_load_dwordx2 v[86:87], v[64:65], off offset:512 nt
	global_load_dwordx2 v[88:89], v[64:65], off offset:1024 nt
	v_lshl_add_u64 v[90:91], v[18:19], 0, s[0:1]
	v_lshl_add_u64 v[92:93], v[20:21], 0, s[0:1]
	global_load_dwordx2 v[94:95], v[90:91], off nt
	global_load_dwordx2 v[96:97], v[90:91], off offset:512 nt
	global_load_dwordx2 v[98:99], v[90:91], off offset:1024 nt
	global_load_dwordx2 v[100:101], v[90:91], off offset:1536 nt
	global_load_dwordx2 v[102:103], v[92:93], off offset:1536 nt
	global_load_dwordx2 v[104:105], v[92:93], off nt
	global_load_dwordx2 v[106:107], v[92:93], off offset:512 nt
	global_load_dwordx2 v[108:109], v[92:93], off offset:1024 nt
	v_lshl_add_u64 v[64:65], v[54:55], 0, s[0:1]
	v_lshl_add_u64 v[60:61], v[56:57], 0, s[0:1]
	s_add_i32 s14, s14, 2
	s_add_u32 s6, s6, 0x1000
	s_addc_u32 s7, s7, 0
	s_add_u32 s8, s8, 0x1000
	s_addc_u32 s9, s9, 0
	s_cmp_lt_i32 s14, s11
	s_waitcnt vmcnt(15)
	v_lshlrev_b32_e32 v90, 16, v72
	v_and_b32_e32 v91, 0xffff0000, v72
	v_lshlrev_b32_e32 v72, 16, v73
	v_and_b32_e32 v73, 0xffff0000, v73
	s_waitcnt vmcnt(14)
	v_lshlrev_b32_e32 v92, 16, v74
	v_and_b32_e32 v93, 0xffff0000, v74
	v_lshlrev_b32_e32 v74, 16, v75
	v_and_b32_e32 v75, 0xffff0000, v75
	s_waitcnt vmcnt(13)
	v_lshlrev_b32_e32 v110, 16, v76
	s_waitcnt vmcnt(11)
	v_lshlrev_b32_e32 v115, 16, v82
	s_waitcnt vmcnt(10)
	v_lshlrev_b32_e32 v118, 16, v84
	v_and_b32_e32 v119, 0xffff0000, v84
	v_lshlrev_b32_e32 v84, 16, v85
	v_and_b32_e32 v85, 0xffff0000, v85
	s_waitcnt vmcnt(9)
	v_lshlrev_b32_e32 v121, 16, v87
	v_lshlrev_b32_e32 v120, 16, v86
	v_and_b32_e32 v87, 0xffff0000, v87
	v_and_b32_e32 v86, 0xffff0000, v86
	s_waitcnt vmcnt(8)
	v_lshlrev_b32_e32 v122, 16, v88
	v_and_b32_e32 v123, 0xffff0000, v88
	v_lshlrev_b32_e32 v88, 16, v89
	v_and_b32_e32 v89, 0xffff0000, v89
	s_waitcnt vmcnt(3)
	v_lshlrev_b32_e32 v133, 16, v102
	v_mul_f32_e32 v114, v85, v85
	v_pk_mul_f32 v[136:137], v[86:87], v[86:87]
	v_mul_f32_e32 v132, v119, v119
	v_mov_b32_e32 v139, v115
	v_mul_f32_e32 v138, v89, v89
	v_mov_b32_e32 v140, v120
	v_mov_b32_e32 v141, v86
	v_mov_b32_e32 v86, v121
	s_waitcnt vmcnt(2)
	v_lshlrev_b32_e32 v142, 16, v104
	v_and_b32_e32 v143, 0xffff0000, v104
	v_lshlrev_b32_e32 v104, 16, v105
	v_and_b32_e32 v105, 0xffff0000, v105
	s_waitcnt vmcnt(1)
	v_lshlrev_b32_e32 v145, 16, v107
	v_lshlrev_b32_e32 v144, 16, v106
	v_and_b32_e32 v107, 0xffff0000, v107
	v_and_b32_e32 v106, 0xffff0000, v106
	v_pk_fma_f32 v[148:149], v[84:85], v[84:85], v[114:115] op_sel_hi:[1,1,0]
	v_pk_fma_f32 v[120:121], v[120:121], v[120:121], v[136:137]
	v_pk_fma_f32 v[136:137], v[118:119], v[118:119], v[132:133] op_sel_hi:[1,1,0]
	v_and_b32_e32 v117, 0xffff0000, v82
	v_lshlrev_b32_e32 v82, 16, v83
	v_and_b32_e32 v83, 0xffff0000, v83
	v_and_b32_e32 v135, 0xffff0000, v102
	v_mul_f32_e32 v134, v123, v123
	v_pk_fma_f32 v[152:153], v[88:89], v[88:89], v[138:139] op_sel_hi:[1,1,0]
	v_mul_f32_e32 v132, v105, v105
	v_pk_mul_f32 v[154:155], v[106:107], v[106:107]
	v_mul_f32_e32 v156, v143, v143
	v_mov_b32_e32 v157, v133
	v_mov_b32_e32 v114, v136
	v_mov_b32_e32 v138, v148
	v_mul_f32_e32 v71, v117, v117
	v_mul_f32_e32 v159, v82, v82
	v_mul_f32_e32 v161, v83, v83
	v_mov_b32_e32 v116, v115
	s_waitcnt vmcnt(0)
	v_lshlrev_b32_e32 v146, 16, v108
	v_and_b32_e32 v147, 0xffff0000, v108
	v_lshlrev_b32_e32 v108, 16, v109
	v_and_b32_e32 v109, 0xffff0000, v109
	v_pk_fma_f32 v[150:151], v[122:123], v[122:123], v[134:135] op_sel_hi:[1,1,0]
	v_mov_b32_e32 v162, v144
	v_mov_b32_e32 v163, v106
	v_mov_b32_e32 v106, v145
	v_pk_add_f32 v[136:137], v[136:137], v[148:149]
	v_pk_add_f32 v[120:121], v[120:121], v[120:121] op_sel:[0,1] op_sel_hi:[1,0]
	v_pk_fma_f32 v[148:149], v[104:105], v[104:105], v[132:133] op_sel_hi:[1,1,0]
	v_pk_fma_f32 v[144:145], v[144:145], v[144:145], v[154:155]
	v_pk_fma_f32 v[154:155], v[142:143], v[142:143], v[156:157] op_sel_hi:[1,1,0]
	v_pk_mul_f32 v[114:115], v[114:115], v[138:139]
	v_lshlrev_b32_e32 v102, 16, v103
	v_and_b32_e32 v103, 0xffff0000, v103
	v_mul_f32_e32 v158, v147, v147
	v_mul_f32_e32 v160, v109, v109
	v_mov_b32_e32 v151, v159
	v_mov_b32_e32 v153, v161
	v_mov_b32_e32 v121, v71
	v_mov_b32_e32 v132, v154
	v_mov_b32_e32 v156, v148
	v_mov_b32_e32 v137, v115
	v_mul_f32_e32 v164, v135, v135
	v_mul_f32_e32 v165, v102, v102
	v_mul_f32_e32 v166, v103, v103
	v_pk_fma_f32 v[158:159], v[146:147], v[146:147], v[158:159] op_sel_hi:[1,1,0]
	v_pk_fma_f32 v[160:161], v[108:109], v[108:109], v[160:161] op_sel_hi:[1,1,0]
	v_pk_add_f32 v[138:139], v[150:151], v[152:153]
	v_pk_add_f32 v[148:149], v[154:155], v[148:149]
	v_pk_add_f32 v[144:145], v[144:145], v[144:145] op_sel:[0,1] op_sel_hi:[1,0]
	v_pk_mul_f32 v[114:115], v[132:133], v[156:157]
	v_pk_add_f32 v[120:121], v[136:137], v[120:121]
	v_mov_b32_e32 v159, v165
	v_mov_b32_e32 v161, v166
	v_mov_b32_e32 v145, v164
	v_mov_b32_e32 v149, v115
	v_pk_add_f32 v[114:115], v[120:121], v[138:139]
	v_mov_b32_e32 v134, v133
	v_pk_add_f32 v[132:133], v[158:159], v[160:161]
	v_pk_add_f32 v[120:121], v[148:149], v[144:145]
	v_add_f32_e32 v71, v114, v115
	v_pk_add_f32 v[114:115], v[120:121], v[132:133]
	ds_bpermute_b32 v121, v59, v71
	v_mov_b32_e32 v120, v114
	v_and_b32_e32 v111, 0xffff0000, v76
	v_lshlrev_b32_e32 v76, 16, v77
	v_and_b32_e32 v77, 0xffff0000, v77
	s_waitcnt lgkmcnt(0)
	v_add_f32_e32 v71, v71, v121
	ds_bpermute_b32 v114, v66, v71
	v_lshlrev_b32_e32 v112, 16, v78
	v_and_b32_e32 v113, 0xffff0000, v78
	v_lshlrev_b32_e32 v78, 16, v79
	v_and_b32_e32 v79, 0xffff0000, v79
	s_waitcnt lgkmcnt(0)
	v_add_f32_e32 v71, v71, v114
	ds_bpermute_b32 v114, v67, v71
	v_lshlrev_b32_e32 v124, 16, v94
	v_and_b32_e32 v125, 0xffff0000, v94
	v_lshlrev_b32_e32 v94, 16, v95
	v_and_b32_e32 v95, 0xffff0000, v95
	s_waitcnt lgkmcnt(0)
	v_add_f32_e32 v71, v71, v114
	ds_bpermute_b32 v114, v68, v71
	v_lshlrev_b32_e32 v126, 16, v96
	v_and_b32_e32 v127, 0xffff0000, v96
	v_lshlrev_b32_e32 v96, 16, v97
	v_and_b32_e32 v97, 0xffff0000, v97
	s_waitcnt lgkmcnt(0)
	v_add_f32_e32 v71, v71, v114
	ds_bpermute_b32 v114, v69, v71
	v_lshlrev_b32_e32 v128, 16, v98
	v_and_b32_e32 v129, 0xffff0000, v98
	v_lshlrev_b32_e32 v98, 16, v99
	v_and_b32_e32 v99, 0xffff0000, v99
	s_waitcnt lgkmcnt(0)
	v_add_f32_e32 v71, v71, v114
	ds_bpermute_b32 v114, v70, v71
	v_lshlrev_b32_e32 v130, 16, v100
	v_and_b32_e32 v131, 0xffff0000, v100
	v_lshlrev_b32_e32 v100, 16, v101
	v_and_b32_e32 v101, 0xffff0000, v101
	s_waitcnt lgkmcnt(0)
	v_add_f32_e32 v71, v71, v114
	v_fmamk_f32 v71, v71, 0x3a800000, v58
	v_mul_f32_e32 v114, 0x4b800000, v71
	v_cmp_gt_f32_e32 vcc, s16, v71
	s_nop 1
	v_cndmask_b32_e32 v71, v71, v114, vcc
	v_rsq_f32_e32 v71, v71
	s_nop 0
	v_mul_f32_e32 v114, 0x45800000, v71
	v_cndmask_b32_e32 v114, v71, v114, vcc
	v_pk_mul_f32 v[118:119], v[114:115], v[118:119] op_sel_hi:[0,1]
	v_pk_mul_f32 v[84:85], v[114:115], v[84:85] op_sel_hi:[0,1]
	v_pk_mul_f32 v[132:133], v[114:115], v[140:141] op_sel_hi:[0,1]
	v_pk_mul_f32 v[86:87], v[114:115], v[86:87] op_sel_hi:[0,1]
	v_pk_mul_f32 v[88:89], v[114:115], v[88:89] op_sel_hi:[0,1]
	v_pk_mul_f32 v[116:117], v[114:115], v[116:117] op_sel_hi:[0,1]
	v_pk_mul_f32 v[82:83], v[114:115], v[82:83] op_sel_hi:[0,1]
	v_pk_mul_f32 v[122:123], v[114:115], v[122:123] op_sel_hi:[0,1]
	v_pk_fma_f32 v[72:73], v[22:23], v[84:85], v[72:73]
	v_pk_fma_f32 v[84:85], v[24:25], v[118:119], v[90:91]
	v_pk_fma_f32 v[74:75], v[26:27], v[86:87], v[74:75]
	v_pk_fma_f32 v[86:87], v[28:29], v[132:133], v[92:93]
	v_pk_fma_f32 v[76:77], v[30:31], v[88:89], v[76:77]
	v_pk_fma_f32 v[78:79], v[34:35], v[82:83], v[78:79]
	v_pk_fma_f32 v[82:83], v[36:37], v[116:117], v[112:113]
	v_pk_fma_f32 v[88:89], v[32:33], v[122:123], v[110:111]
	v_cvt_pk_bf16_f32 v84, v84, v85
	v_cvt_pk_bf16_f32 v85, v72, v73
	v_cvt_pk_bf16_f32 v72, v86, v87
	v_cvt_pk_bf16_f32 v73, v74, v75
	v_cvt_pk_bf16_f32 v75, v76, v77
	v_cvt_pk_bf16_f32 v76, v82, v83
	v_cvt_pk_bf16_f32 v77, v78, v79
	v_cvt_pk_bf16_f32 v74, v88, v89
	global_store_dwordx2 v[80:81], v[84:85], off nt
	global_store_dwordx2 v[80:81], v[72:73], off offset:512 nt
	global_store_dwordx2 v[80:81], v[74:75], off offset:1024 nt
	global_store_dwordx2 v[80:81], v[76:77], off offset:1536 nt
	v_lshlrev_b32_e32 v81, 16, v85
	v_lshlrev_b32_e32 v80, 16, v84
	v_and_b32_e32 v83, 0xffff0000, v85
	v_and_b32_e32 v82, 0xffff0000, v84
	v_lshlrev_b32_e32 v85, 16, v73
	v_lshlrev_b32_e32 v84, 16, v72
	v_and_b32_e32 v73, 0xffff0000, v73
	v_and_b32_e32 v72, 0xffff0000, v72
	v_lshlrev_b32_e32 v78, 16, v74
	v_and_b32_e32 v79, 0xffff0000, v74
	v_lshlrev_b32_e32 v74, 16, v76
	v_lshlrev_b32_e32 v86, 16, v75
	v_pk_mul_f32 v[88:89], v[82:83], v[82:83]
	v_pk_mul_f32 v[90:91], v[72:73], v[72:73]
	v_and_b32_e32 v87, 0xffff0000, v75
	v_mul_f32_e32 v75, v78, v78
	v_mul_f32_e32 v93, v79, v79
	v_mul_f32_e32 v110, v86, v86
	v_mov_b32_e32 v92, v74
	v_mov_b32_e32 v116, v80
	v_mov_b32_e32 v117, v82
	v_mov_b32_e32 v82, v81
	v_mov_b32_e32 v118, v84
	v_mov_b32_e32 v119, v72
	v_mov_b32_e32 v72, v85
	v_pk_fma_f32 v[80:81], v[80:81], v[80:81], v[88:89]
	v_pk_fma_f32 v[84:85], v[84:85], v[84:85], v[90:91]
	v_and_b32_e32 v71, 0xffff0000, v76
	v_lshlrev_b32_e32 v76, 16, v77
	v_and_b32_e32 v77, 0xffff0000, v77
	v_pk_fma_f32 v[88:89], v[86:87], v[86:87], v[110:111] op_sel_hi:[1,1,0]
	v_pk_add_f32 v[90:91], v[74:75], v[92:93]
	v_pk_add_f32 v[80:81], v[80:81], v[80:81] op_sel_hi:[0,1]
	v_pk_add_f32 v[84:85], v[84:85], v[84:85] op_sel_hi:[0,1]
	v_mul_f32_e32 v112, v74, v74
	v_mul_f32_e32 v88, v71, v71
	v_mov_b32_e32 v113, v91
	v_mul_f32_e32 v80, v76, v76
	v_mul_f32_e32 v84, v77, v77
	v_pk_add_f32 v[88:89], v[112:113], v[88:89]
	v_pk_add_f32 v[80:81], v[80:81], v[84:85]
	v_mov_b32_e32 v75, v71
	v_pk_add_f32 v[80:81], v[88:89], v[80:81]
	s_nop 0
	v_mov_b32_e32 v121, v80
	v_mov_b32_e32 v80, v115
	v_pk_add_f32 v[80:81], v[120:121], v[80:81]
	ds_bpermute_b32 v85, v59, v81
	ds_bpermute_b32 v84, v59, v80
	s_waitcnt lgkmcnt(0)
	v_pk_add_f32 v[80:81], v[80:81], v[84:85]
	ds_bpermute_b32 v85, v66, v81
	ds_bpermute_b32 v84, v66, v80
	s_waitcnt lgkmcnt(0)
	v_pk_add_f32 v[80:81], v[80:81], v[84:85]
	ds_bpermute_b32 v85, v67, v81
	ds_bpermute_b32 v84, v67, v80
	s_waitcnt lgkmcnt(0)
	v_pk_add_f32 v[80:81], v[80:81], v[84:85]
	ds_bpermute_b32 v85, v68, v81
	ds_bpermute_b32 v84, v68, v80
	s_waitcnt lgkmcnt(0)
	v_pk_add_f32 v[80:81], v[80:81], v[84:85]
	ds_bpermute_b32 v85, v69, v81
	ds_bpermute_b32 v84, v69, v80
	s_waitcnt lgkmcnt(0)
	v_pk_add_f32 v[80:81], v[80:81], v[84:85]
	ds_bpermute_b32 v85, v70, v81
	ds_bpermute_b32 v84, v70, v80
	s_waitcnt lgkmcnt(0)
	v_pk_add_f32 v[80:81], v[80:81], v[84:85]
	s_nop 0
	v_pk_fma_f32 v[80:81], v[80:81], s[10:11], v[58:59] op_sel_hi:[1,0,0]
	s_nop 0
	v_mul_f32_e32 v71, 0x4b800000, v81
	v_mul_f32_e32 v84, 0x4b800000, v80
	v_cmp_gt_f32_e32 vcc, s16, v80
	v_cmp_gt_f32_e64 s[0:1], s16, v81
	s_nop 0
	v_cndmask_b32_e32 v80, v80, v84, vcc
	v_cndmask_b32_e64 v71, v81, v71, s[0:1]
	v_rsq_f32_e32 v71, v71
	v_rsq_f32_e32 v81, v80
	v_mul_f32_e32 v80, 0x45800000, v71
	v_mul_f32_e32 v84, 0x45800000, v81
	v_cndmask_b32_e64 v80, v71, v80, s[0:1]
	v_cndmask_b32_e32 v84, v81, v84, vcc
	v_pk_mul_f32 v[88:89], v[80:81], v[116:117] op_sel_hi:[0,1]
	v_pk_mul_f32 v[82:83], v[80:81], v[82:83] op_sel_hi:[0,1]
	v_pk_mul_f32 v[90:91], v[80:81], v[118:119] op_sel_hi:[0,1]
	v_pk_mul_f32 v[72:73], v[80:81], v[72:73] op_sel_hi:[0,1]
	v_pk_mul_f32 v[78:79], v[80:81], v[78:79] op_sel_hi:[0,1]
	v_pk_mul_f32 v[86:87], v[80:81], v[86:87] op_sel_hi:[0,1]
	v_pk_mul_f32 v[74:75], v[80:81], v[74:75] op_sel_hi:[0,1]
	v_pk_mul_f32 v[76:77], v[80:81], v[76:77] op_sel_hi:[0,1]
	v_pk_mul_f32 v[80:81], v[84:85], v[142:143] op_sel_hi:[0,1]
	v_pk_mul_f32 v[92:93], v[84:85], v[104:105] op_sel_hi:[0,1]
	v_pk_mul_f32 v[104:105], v[84:85], v[162:163] op_sel_hi:[0,1]
	v_pk_mul_f32 v[106:107], v[84:85], v[106:107] op_sel_hi:[0,1]
	v_pk_mul_f32 v[110:111], v[84:85], v[146:147] op_sel_hi:[0,1]
	v_pk_mul_f32 v[108:109], v[84:85], v[108:109] op_sel_hi:[0,1]
	v_pk_mul_f32 v[112:113], v[84:85], v[134:135] op_sel_hi:[0,1]
	v_pk_mul_f32 v[84:85], v[84:85], v[102:103] op_sel_hi:[0,1]
	v_pk_fma_f32 v[82:83], v[38:39], v[82:83], v[2:3]
	v_pk_fma_f32 v[88:89], v[40:41], v[88:89], v[0:1]
	v_pk_fma_f32 v[72:73], v[42:43], v[72:73], v[6:7]
	v_pk_fma_f32 v[90:91], v[44:45], v[90:91], v[4:5]
	v_pk_fma_f32 v[78:79], v[48:49], v[78:79], v[8:9]
	v_pk_fma_f32 v[76:77], v[50:51], v[76:77], v[14:15]
	v_pk_fma_f32 v[74:75], v[52:53], v[74:75], v[12:13]
	v_pk_fma_f32 v[92:93], v[22:23], v[92:93], v[94:95]
	v_pk_fma_f32 v[80:81], v[24:25], v[80:81], v[124:125]
	v_pk_fma_f32 v[94:95], v[26:27], v[106:107], v[96:97]
	v_pk_fma_f32 v[96:97], v[28:29], v[104:105], v[126:127]
	v_pk_fma_f32 v[86:87], v[46:47], v[86:87], v[10:11]
	v_pk_fma_f32 v[98:99], v[30:31], v[108:109], v[98:99]
	v_pk_fma_f32 v[102:103], v[32:33], v[110:111], v[128:129]
	v_pk_fma_f32 v[84:85], v[34:35], v[84:85], v[100:101]
	v_pk_fma_f32 v[100:101], v[36:37], v[112:113], v[130:131]
	v_cvt_pk_bf16_f32 v88, v88, v89
	v_cvt_pk_bf16_f32 v89, v82, v83
	v_cvt_pk_bf16_f32 v82, v90, v91
	v_cvt_pk_bf16_f32 v83, v72, v73
	v_cvt_pk_bf16_f32 v72, v78, v79
	v_cvt_pk_bf16_f32 v74, v74, v75
	v_cvt_pk_bf16_f32 v75, v76, v77
	v_cvt_pk_bf16_f32 v76, v80, v81
	v_cvt_pk_bf16_f32 v77, v92, v93
	v_cvt_pk_bf16_f32 v78, v96, v97
	v_cvt_pk_bf16_f32 v79, v94, v95
	v_cvt_pk_bf16_f32 v73, v86, v87
	v_cvt_pk_bf16_f32 v80, v102, v103
	v_cvt_pk_bf16_f32 v81, v98, v99
	v_cvt_pk_bf16_f32 v86, v100, v101
	v_cvt_pk_bf16_f32 v87, v84, v85
	global_store_dwordx2 v[62:63], v[88:89], off
	global_store_dwordx2 v[62:63], v[82:83], off offset:512
	global_store_dwordx2 v[62:63], v[72:73], off offset:1024
	global_store_dwordx2 v[62:63], v[74:75], off offset:1536
	global_store_dwordx2 v[64:65], v[76:77], off nt
	global_store_dwordx2 v[64:65], v[78:79], off offset:512 nt
	global_store_dwordx2 v[64:65], v[80:81], off offset:1024 nt
	v_lshlrev_b32_e32 v75, 16, v77
	v_lshlrev_b32_e32 v74, 16, v76
	v_and_b32_e32 v77, 0xffff0000, v77
	v_and_b32_e32 v76, 0xffff0000, v76
	v_lshlrev_b32_e32 v83, 16, v79
	v_lshlrev_b32_e32 v82, 16, v78
	v_and_b32_e32 v79, 0xffff0000, v79
	v_and_b32_e32 v78, 0xffff0000, v78
	v_lshlrev_b32_e32 v62, 16, v80
	v_and_b32_e32 v63, 0xffff0000, v80
	global_store_dwordx2 v[64:65], v[86:87], off offset:1536 nt
	v_lshlrev_b32_e32 v64, 16, v86
	v_and_b32_e32 v71, 0xffff0000, v86
	v_lshlrev_b32_e32 v72, 16, v87
	v_and_b32_e32 v73, 0xffff0000, v87
	v_lshlrev_b32_e32 v80, 16, v81
	v_pk_mul_f32 v[84:85], v[76:77], v[76:77]
	v_pk_mul_f32 v[86:87], v[78:79], v[78:79]
	v_and_b32_e32 v81, 0xffff0000, v81
	v_mul_f32_e32 v65, v62, v62
	v_mul_f32_e32 v89, v63, v63
	v_mul_f32_e32 v90, v80, v80
	v_mov_b32_e32 v88, v64
	v_mov_b32_e32 v94, v74
	v_mov_b32_e32 v95, v76
	v_mov_b32_e32 v76, v75
	v_mov_b32_e32 v96, v82
	v_mov_b32_e32 v97, v78
	v_mov_b32_e32 v78, v83
	v_pk_fma_f32 v[74:75], v[74:75], v[74:75], v[84:85]
	v_pk_fma_f32 v[82:83], v[82:83], v[82:83], v[86:87]
	v_pk_fma_f32 v[84:85], v[80:81], v[80:81], v[90:91] op_sel_hi:[1,1,0]
	v_pk_add_f32 v[86:87], v[64:65], v[88:89]
	v_pk_add_f32 v[74:75], v[74:75], v[74:75] op_sel_hi:[0,1]
	v_pk_add_f32 v[82:83], v[82:83], v[82:83] op_sel_hi:[0,1]
	v_mul_f32_e32 v92, v64, v64
	v_mul_f32_e32 v84, v71, v71
	v_mov_b32_e32 v93, v87
	v_mul_f32_e32 v74, v72, v72
	v_mul_f32_e32 v82, v73, v73
	v_pk_add_f32 v[84:85], v[92:93], v[84:85]
	v_pk_add_f32 v[74:75], v[74:75], v[82:83]
	v_mov_b32_e32 v65, v71
	v_pk_add_f32 v[74:75], v[84:85], v[74:75]
	s_nop 0
	v_add_f32_e32 v71, v74, v75
	ds_bpermute_b32 v74, v59, v71
	s_waitcnt lgkmcnt(0)
	v_add_f32_e32 v71, v71, v74
	ds_bpermute_b32 v74, v66, v71
	s_waitcnt lgkmcnt(0)
	v_add_f32_e32 v71, v71, v74
	ds_bpermute_b32 v74, v67, v71
	s_waitcnt lgkmcnt(0)
	v_add_f32_e32 v71, v71, v74
	ds_bpermute_b32 v74, v68, v71
	s_waitcnt lgkmcnt(0)
	v_add_f32_e32 v71, v71, v74
	ds_bpermute_b32 v74, v69, v71
	s_waitcnt lgkmcnt(0)
	v_add_f32_e32 v71, v71, v74
	ds_bpermute_b32 v74, v70, v71
	s_waitcnt lgkmcnt(0)
	v_add_f32_e32 v71, v71, v74
	v_fmamk_f32 v71, v71, 0x3a800000, v58
	v_mul_f32_e32 v74, 0x4b800000, v71
	v_cmp_gt_f32_e32 vcc, s16, v71
	s_nop 1
	v_cndmask_b32_e32 v71, v71, v74, vcc
	v_rsq_f32_e32 v71, v71
	s_nop 0
	v_mul_f32_e32 v74, 0x45800000, v71
	v_cndmask_b32_e32 v74, v71, v74, vcc
	v_pk_mul_f32 v[82:83], v[74:75], v[94:95] op_sel_hi:[0,1]
	v_pk_mul_f32 v[76:77], v[74:75], v[76:77] op_sel_hi:[0,1]
	v_pk_mul_f32 v[84:85], v[74:75], v[96:97] op_sel_hi:[0,1]
	v_pk_mul_f32 v[78:79], v[74:75], v[78:79] op_sel_hi:[0,1]
	v_pk_mul_f32 v[62:63], v[74:75], v[62:63] op_sel_hi:[0,1]
	v_pk_mul_f32 v[80:81], v[74:75], v[80:81] op_sel_hi:[0,1]
	v_pk_mul_f32 v[64:65], v[74:75], v[64:65] op_sel_hi:[0,1]
	v_pk_mul_f32 v[72:73], v[74:75], v[72:73] op_sel_hi:[0,1]
	v_pk_fma_f32 v[74:75], v[38:39], v[76:77], v[2:3]
	v_pk_fma_f32 v[76:77], v[40:41], v[82:83], v[0:1]
	v_pk_fma_f32 v[78:79], v[42:43], v[78:79], v[6:7]
	v_pk_fma_f32 v[82:83], v[44:45], v[84:85], v[4:5]
	v_pk_fma_f32 v[80:81], v[46:47], v[80:81], v[10:11]
	v_pk_fma_f32 v[62:63], v[48:49], v[62:63], v[8:9]
	v_pk_fma_f32 v[72:73], v[50:51], v[72:73], v[14:15]
	v_pk_fma_f32 v[64:65], v[52:53], v[64:65], v[12:13]
	v_cvt_pk_bf16_f32 v76, v76, v77
	v_cvt_pk_bf16_f32 v77, v74, v75
	v_cvt_pk_bf16_f32 v74, v82, v83
	v_cvt_pk_bf16_f32 v75, v78, v79
	v_cvt_pk_bf16_f32 v62, v62, v63
	v_cvt_pk_bf16_f32 v63, v80, v81
	v_cvt_pk_bf16_f32 v64, v64, v65
	v_cvt_pk_bf16_f32 v65, v72, v73
	global_store_dwordx2 v[60:61], v[76:77], off
	global_store_dwordx2 v[60:61], v[74:75], off offset:512
	global_store_dwordx2 v[60:61], v[62:63], off offset:1024
	global_store_dwordx2 v[60:61], v[64:65], off offset:1536
	s_cbranch_scc1 .LBB0_1498
